# v31: v22 + attention softmax subtractions as 16 v_pk_add_f32 (max broadcast, negated) instead of 32 v_sub_f32, exp in place
# baseline (speedup 1.0000x reference)
; DI unsigned pack2(float a, float b) { f2_t v = {a, b}; bf2_t r = __builtin_convertvector(v, bf2_t); return __builtin_bit_cast(unsigned, r); }
; DI float fexp2(float x) { return __builtin_amdgcn_exp2f(x); }
; template <int PM> DI void attn_phase(const Params& p, int l, char* smem, int* s_item, int wv, int cidx) {
;     ...
;           float ps = 0.f;
; #pragma unroll
;           for (int kb = 0; kb < 2; ++kb)
; #pragma unroll
;             for (int e = 0; e < 16; ++e) { const float pv = fexp2(sacc[kb][e] - m); sacc[kb][e] = pv; ps += pv; }
;           lsum += ps;
; #pragma unroll
;           for (int kb = 0; kb < 2; ++kb)
; #pragma unroll
;             for (int s2 = 0; s2 < 2; ++s2) {
;               u32x4 t;
;               t[0] = pack2(sacc[kb][8 * s2 + 0], sacc[kb][8 * s2 + 1]);
;               t[1] = pack2(sacc[kb][8 * s2 + 2], sacc[kb][8 * s2 + 3]);
;               t[2] = pack2(sacc[kb][8 * s2 + 4], sacc[kb][8 * s2 + 5]);
;               t[3] = pack2(sacc[kb][8 * s2 + 6], sacc[kb][8 * s2 + 7]);
;               pf[kb][s2] = __builtin_bit_cast(bf16x8, t);
;             }
;           if (!shift) ATT_PV_RUN(vcur); else pend = true;
.LBB0_514:
	v_pk_add_f32 v[16:17], v[16:17], v[232:233] op_sel:[0,1] op_sel_hi:[1,1] neg_lo:[0,1] neg_hi:[0,1]
	v_exp_f32_e32 v16, v16
	v_exp_f32_e32 v17, v17
	v_pk_add_f32 v[18:19], v[18:19], v[232:233] op_sel:[0,1] op_sel_hi:[1,1] neg_lo:[0,1] neg_hi:[0,1]
	v_exp_f32_e32 v18, v18
	v_exp_f32_e32 v19, v19
	v_add_f32_e32 v0, 0, v16
	v_add_f32_e32 v0, v17, v0
	v_pk_add_f32 v[20:21], v[20:21], v[232:233] op_sel:[0,1] op_sel_hi:[1,1] neg_lo:[0,1] neg_hi:[0,1]
	v_exp_f32_e32 v20, v20
	v_exp_f32_e32 v21, v21
	v_add_f32_e32 v0, v18, v0
	v_add_f32_e32 v0, v19, v0
	v_pk_add_f32 v[22:23], v[22:23], v[232:233] op_sel:[0,1] op_sel_hi:[1,1] neg_lo:[0,1] neg_hi:[0,1]
	v_exp_f32_e32 v22, v22
	v_exp_f32_e32 v23, v23
	v_add_f32_e32 v0, v20, v0
	v_add_f32_e32 v0, v21, v0
	v_pk_add_f32 v[24:25], v[24:25], v[232:233] op_sel:[0,1] op_sel_hi:[1,1] neg_lo:[0,1] neg_hi:[0,1]
	v_exp_f32_e32 v24, v24
	v_exp_f32_e32 v25, v25
	v_add_f32_e32 v0, v22, v0
	v_add_f32_e32 v0, v23, v0
	v_pk_add_f32 v[26:27], v[26:27], v[232:233] op_sel:[0,1] op_sel_hi:[1,1] neg_lo:[0,1] neg_hi:[0,1]
	v_exp_f32_e32 v26, v26
	v_exp_f32_e32 v27, v27
	v_add_f32_e32 v0, v24, v0
	v_add_f32_e32 v0, v25, v0
	v_pk_add_f32 v[28:29], v[28:29], v[232:233] op_sel:[0,1] op_sel_hi:[1,1] neg_lo:[0,1] neg_hi:[0,1]
	v_exp_f32_e32 v28, v28
	v_exp_f32_e32 v29, v29
	v_add_f32_e32 v0, v26, v0
	v_add_f32_e32 v0, v27, v0
	v_pk_add_f32 v[30:31], v[30:31], v[232:233] op_sel:[0,1] op_sel_hi:[1,1] neg_lo:[0,1] neg_hi:[0,1]
	v_exp_f32_e32 v30, v30
	v_exp_f32_e32 v31, v31
	v_add_f32_e32 v0, v28, v0
	v_add_f32_e32 v0, v29, v0
	v_pk_add_f32 v[32:33], v[32:33], v[232:233] op_sel:[0,1] op_sel_hi:[1,1] neg_lo:[0,1] neg_hi:[0,1]
	v_exp_f32_e32 v32, v32
	v_exp_f32_e32 v33, v33
	v_add_f32_e32 v0, v30, v0
	v_add_f32_e32 v0, v31, v0
	v_pk_add_f32 v[34:35], v[34:35], v[232:233] op_sel:[0,1] op_sel_hi:[1,1] neg_lo:[0,1] neg_hi:[0,1]
	v_exp_f32_e32 v34, v34
	v_exp_f32_e32 v35, v35
	v_add_f32_e32 v0, v32, v0
	v_add_f32_e32 v0, v33, v0
	v_pk_add_f32 v[36:37], v[36:37], v[232:233] op_sel:[0,1] op_sel_hi:[1,1] neg_lo:[0,1] neg_hi:[0,1]
	v_exp_f32_e32 v36, v36
	v_exp_f32_e32 v37, v37
	v_add_f32_e32 v0, v34, v0
	v_add_f32_e32 v0, v35, v0
	v_pk_add_f32 v[38:39], v[38:39], v[232:233] op_sel:[0,1] op_sel_hi:[1,1] neg_lo:[0,1] neg_hi:[0,1]
	v_exp_f32_e32 v38, v38
	v_exp_f32_e32 v39, v39
	v_add_f32_e32 v0, v36, v0
	v_add_f32_e32 v0, v37, v0
	v_pk_add_f32 v[40:41], v[40:41], v[232:233] op_sel:[0,1] op_sel_hi:[1,1] neg_lo:[0,1] neg_hi:[0,1]
	v_exp_f32_e32 v40, v40
	v_exp_f32_e32 v41, v41
	v_add_f32_e32 v0, v38, v0
	v_pk_add_f32 v[42:43], v[42:43], v[232:233] op_sel:[0,1] op_sel_hi:[1,1] neg_lo:[0,1] neg_hi:[0,1]
	v_exp_f32_e32 v42, v42
	v_exp_f32_e32 v43, v43
	v_pk_add_f32 v[44:45], v[44:45], v[232:233] op_sel:[0,1] op_sel_hi:[1,1] neg_lo:[0,1] neg_hi:[0,1]
	v_exp_f32_e32 v44, v44
	v_exp_f32_e32 v45, v45
	v_pk_add_f32 v[46:47], v[46:47], v[232:233] op_sel:[0,1] op_sel_hi:[1,1] neg_lo:[0,1] neg_hi:[0,1]
	v_exp_f32_e32 v46, v46
	v_exp_f32_e32 v47, v47
	v_add_u32_e32 v14, s95, v242
	v_cvt_pk_bf16_f32 v2, v16, v17
	v_cvt_pk_bf16_f32 v3, v18, v19
	v_cvt_pk_bf16_f32 v4, v20, v21
	v_cvt_pk_bf16_f32 v5, v22, v23
	ds_read_b64_tr_b16 v[52:53], v14 offset:39936
	ds_read_b64_tr_b16 v[54:55], v14 offset:42496
	ds_read_b64_tr_b16 v[56:57], v14 offset:45056
	ds_read_b64_tr_b16 v[58:59], v14 offset:47616
	ds_read_b64_tr_b16 v[60:61], v14 offset:50176
	ds_read_b64_tr_b16 v[62:63], v14 offset:52736
	v_add_f32_e32 v0, v39, v0
	s_waitcnt lgkmcnt(6)
	v_mfma_f32_32x32x16_bf16 v[128:143], v[144:147], v[2:5], v[128:143]
	v_add_f32_e32 v0, v40, v0
	v_add_f32_e32 v0, v41, v0
	v_add_f32_e32 v0, v42, v0
	ds_read_b64_tr_b16 v[64:65], v14 offset:34880
	ds_read_b64_tr_b16 v[66:67], v14 offset:37440
	v_add_f32_e32 v0, v43, v0
	v_add_f32_e32 v0, v44, v0
	v_add_f32_e32 v0, v45, v0
	v_add_f32_e32 v0, v46, v0
	v_add_f32_e32 v0, v47, v0
	v_cvt_pk_bf16_f32 v6, v24, v25
	v_cvt_pk_bf16_f32 v7, v26, v27
	v_cvt_pk_bf16_f32 v8, v28, v29
	v_cvt_pk_bf16_f32 v9, v30, v31
	v_cvt_pk_bf16_f32 v10, v32, v33
	v_cvt_pk_bf16_f32 v11, v34, v35
	v_cvt_pk_bf16_f32 v12, v36, v37
	v_cvt_pk_bf16_f32 v13, v38, v39
	v_cvt_pk_bf16_f32 v48, v40, v41
	v_cvt_pk_bf16_f32 v49, v42, v43
	v_cvt_pk_bf16_f32 v50, v44, v45
	v_cvt_pk_bf16_f32 v51, v46, v47
	s_waitcnt lgkmcnt(6)
	v_mfma_f32_32x32x16_bf16 v[128:143], v[52:55], v[6:9], v[128:143]
	ds_read_b64_tr_b16 v[52:53], v14 offset:40000
	ds_read_b64_tr_b16 v[54:55], v14 offset:42560
	s_waitcnt lgkmcnt(6)
	v_mfma_f32_32x32x16_bf16 v[128:143], v[56:59], v[10:13], v[128:143]
	ds_read_b64_tr_b16 v[56:57], v14 offset:45120
	ds_read_b64_tr_b16 v[58:59], v14 offset:47680
	s_waitcnt lgkmcnt(6)
	v_mfma_f32_32x32x16_bf16 v[128:143], v[60:63], v[48:51], v[128:143]
	ds_read_b64_tr_b16 v[60:61], v14 offset:50240
	ds_read_b64_tr_b16 v[62:63], v14 offset:52800
	s_waitcnt lgkmcnt(6)
	v_mfma_f32_32x32x16_bf16 v[112:127], v[64:67], v[2:5], v[112:127]
	ds_read_b64_tr_b16 v[64:65], v14 offset:34944
	ds_read_b64_tr_b16 v[66:67], v14 offset:37504
	s_waitcnt lgkmcnt(6)
	v_mfma_f32_32x32x16_bf16 v[112:127], v[52:55], v[6:9], v[112:127]
	ds_read_b64_tr_b16 v[52:53], v14 offset:40064
	ds_read_b64_tr_b16 v[54:55], v14 offset:42624
	s_waitcnt lgkmcnt(6)
	v_mfma_f32_32x32x16_bf16 v[112:127], v[56:59], v[10:13], v[112:127]
	ds_read_b64_tr_b16 v[56:57], v14 offset:45184
	ds_read_b64_tr_b16 v[58:59], v14 offset:47744
	s_waitcnt lgkmcnt(6)
	v_mfma_f32_32x32x16_bf16 v[112:127], v[60:63], v[48:51], v[112:127]
	ds_read_b64_tr_b16 v[60:61], v14 offset:50304
	ds_read_b64_tr_b16 v[62:63], v14 offset:52864
	s_waitcnt lgkmcnt(6)
	v_mfma_f32_32x32x16_bf16 v[96:111], v[64:67], v[2:5], v[96:111]
	ds_read_b64_tr_b16 v[144:145], v14 offset:35008
	ds_read_b64_tr_b16 v[146:147], v14 offset:37568
	s_waitcnt lgkmcnt(6)
	v_mfma_f32_32x32x16_bf16 v[96:111], v[52:55], v[6:9], v[96:111]
	ds_read_b64_tr_b16 v[52:53], v14 offset:40128
	ds_read_b64_tr_b16 v[54:55], v14 offset:42688
	s_waitcnt lgkmcnt(6)
	v_mfma_f32_32x32x16_bf16 v[96:111], v[56:59], v[10:13], v[96:111]
	ds_read_b64_tr_b16 v[56:57], v14 offset:45248
	ds_read_b64_tr_b16 v[58:59], v14 offset:47808
	s_waitcnt lgkmcnt(6)
	v_mfma_f32_32x32x16_bf16 v[96:111], v[60:63], v[48:51], v[96:111]
	ds_read_b64_tr_b16 v[60:61], v14 offset:50368
	ds_read_b64_tr_b16 v[62:63], v14 offset:52928
	s_waitcnt lgkmcnt(6)
	v_mfma_f32_32x32x16_bf16 v[80:95], v[144:147], v[2:5], v[80:95]
	s_waitcnt lgkmcnt(4)
	v_mfma_f32_32x32x16_bf16 v[80:95], v[52:55], v[6:9], v[80:95]
	s_waitcnt lgkmcnt(2)
	v_mfma_f32_32x32x16_bf16 v[80:95], v[56:59], v[10:13], v[80:95]
	s_waitcnt lgkmcnt(0)
	v_mfma_f32_32x32x16_bf16 v[80:95], v[60:63], v[48:51], v[80:95]
	v_add_f32_e32 v235, v235, v0
